# release s_barrier of every grid barrier sunk below the next phase's ALU-only prologue, now also past kernel-argument s_loads (MIX/Q2/FINAL prologues)
# baseline (speedup 1.0000x reference)
.LBB0_236:
	v_writelane_b32 v255, s74, 26
	s_nop 1
	v_writelane_b32 v255, s75, 27
	v_writelane_b32 v255, s72, 28
	s_nop 1
	v_writelane_b32 v255, s73, 29
	v_writelane_b32 v255, s68, 30
	s_or_b64 exec, exec, s[4:5]
	s_waitcnt lgkmcnt(0)
	v_mov_b32_e32 v0, 0
	s_mov_b32 s84, s70
	v_mbcnt_lo_u32_b32 v0, -1, v0
	v_mbcnt_hi_u32_b32 v0, -1, v0
	v_add_u32_e32 v97, s33, v0
	v_cndmask_b32_e64 v0, 0, 1, s[14:15]
	v_readfirstlane_b32 s1, v97
	s_ashr_i32 s89, s1, 6
	s_add_u32 s2, s82, 0xdae7300
	v_writelane_b32 v255, s2, 31
	s_addc_u32 s2, s83, 0
	v_writelane_b32 v255, s2, 33
	s_add_u32 s2, s82, 0x11be7300
	v_writelane_b32 v255, s2, 35
	s_addc_u32 s2, s83, 0
	v_writelane_b32 v255, s2, 37
	s_mov_b32 s2, 0
	s_ashr_i32 s3, s2, 31
	s_lshl_b64 s[2:3], s[2:3], 3
	v_readlane_b32 s6, v255, 2
	v_readlane_b32 s7, v255, 3
	s_add_u32 s2, s6, s2
	s_addc_u32 s3, s7, s3
	s_load_dwordx2 s[2:3], s[2:3], 0x38
	s_mov_b32 s5, 0
	v_mov_b32_e32 v67, 0
	v_and_b32_e32 v96, 63, v97
	v_lshlrev_b32_e32 v64, 3, v97
	s_waitcnt lgkmcnt(0)
	v_writelane_b32 v255, s2, 39
	s_nop 1
	v_writelane_b32 v255, s3, 40
	s_mov_b32 s2, 0
	s_ashr_i32 s3, s2, 31
	s_lshl_b64 s[2:3], s[2:3], 3
	s_add_u32 s2, s6, s2
	s_addc_u32 s3, s7, s3
	s_load_dwordx2 s[2:3], s[2:3], 0x40
	s_waitcnt lgkmcnt(0)
	v_writelane_b32 v255, s2, 41
	s_nop 1
	v_writelane_b32 v255, s3, 42
	s_mov_b32 s2, 0
	s_ashr_i32 s3, s2, 31
	s_lshl_b64 s[2:3], s[2:3], 3
	s_add_u32 s2, s6, s2
	s_addc_u32 s3, s7, s3
	s_load_dwordx2 s[96:97], s[2:3], 0x48
	v_cmp_ne_u32_e64 s[2:3], 1, v0
	s_andn2_b64 vcc, exec, s[14:15]
	s_nop 0
	v_writelane_b32 v255, s2, 43
	s_nop 1
	v_writelane_b32 v255, s3, 44
	s_cbranch_vccz .Lmy_bsk2
	s_barrier
	s_branch .LBB0_305
.Lmy_bsk2:
	v_and_b32_e32 v0, 3, v97
	v_lshlrev_b32_e32 v5, 5, v0
	v_lshlrev_b32_e32 v66, 7, v0
	v_lshlrev_b32_e32 v9, 2, v0
	v_lshrrev_b32_e32 v0, 3, v97
	s_lshl_b32 s3, s89, 2
	v_and_b32_e32 v0, 2, v0
	v_bfe_u32 v2, v97, 1, 1
	v_bfe_u32 v3, v97, 2, 2
	v_or3_b32 v0, s3, v0, v2
	s_movk_i32 s2, 0x80
	v_lshlrev_b32_e32 v2, 6, v3
	v_lshlrev_b32_e32 v0, 4, v0
	v_cmp_gt_i32_e32 vcc, s2, v97
	s_add_i32 s2, 0, 0x18000
	v_xad_u32 v13, v0, v2, 0
	v_lshlrev_b32_e32 v0, 8, v97
	v_lshl_add_u32 v98, v97, 2, s2
	v_ashrrev_i32_e32 v68, 2, v97
	v_add_u32_e32 v99, s2, v66
	s_add_i32 s2, 0, 0x10000
	v_and_b32_e32 v0, 0x1f00, v0
	v_readlane_b32 s6, v255, 41
	v_lshl_add_u32 v7, v68, 8, s2
	v_add_u32_e32 v16, s2, v0
	s_lshl_b32 s2, s89, 5
	v_readlane_b32 s7, v255, 42
	s_ashr_i32 s3, s2, 31
	v_readlane_b32 s4, v255, 31
	v_lshl_add_u64 v[70:71], s[6:7], 0, v[66:67]
	s_lshl_b64 s[6:7], s[2:3], 1
	v_lshrrev_b32_e32 v1, 5, v96
	s_add_u32 s6, s4, s6
	v_readlane_b32 s4, v255, 33
	s_addc_u32 s7, s4, s7
	v_lshlrev_b32_e32 v66, 3, v1
	v_lshl_add_u64 v[72:73], s[6:7], 0, v[66:67]
	s_lshl_b64 s[2:3], s[2:3], 2
	v_readlane_b32 s6, v255, 39
	v_or_b32_e32 v19, 8, v5
	v_or_b32_e32 v20, 16, v5
	v_readlane_b32 s7, v255, 40
	s_add_u32 s2, s6, s2
	v_cmp_le_i32_e64 s[24:25], v19, v68
	v_or_b32_e32 v19, 9, v5
	v_cmp_le_i32_e64 s[42:43], v20, v68
	v_or_b32_e32 v20, 17, v5
	v_or_b32_e32 v21, 24, v5
	s_addc_u32 s3, s7, s3
	s_add_i32 s6, s89, 32
	v_or_b32_e32 v18, 2, v5
	v_cmp_le_i32_e64 s[26:27], v19, v68
	v_or_b32_e32 v19, 10, v5
	v_cmp_le_i32_e64 s[44:45], v20, v68
	v_or_b32_e32 v20, 18, v5
	v_cmp_le_i32_e64 s[58:59], v21, v68
	v_or_b32_e32 v21, 25, v5
	v_lshl_or_b32 v8, s6, 6, v96
	s_lshl_b32 s8, s6, 10
	s_add_i32 s6, s89, 40
	v_cmp_le_i32_e64 s[12:13], v18, v68
	v_or_b32_e32 v18, 3, v5
	v_cmp_le_i32_e64 s[28:29], v19, v68
	v_or_b32_e32 v19, 11, v5
	v_cmp_le_i32_e64 s[46:47], v20, v68
	v_or_b32_e32 v20, 19, v5
	v_cmp_le_i32_e64 s[60:61], v21, v68
	v_or_b32_e32 v21, 26, v5
	v_lshlrev_b32_e32 v66, 4, v1
	v_lshl_or_b32 v10, s6, 6, v96
	s_lshl_b32 s9, s6, 10
	s_add_i32 s6, s89, 48
	v_cmp_le_i32_e64 s[14:15], v18, v68
	v_or_b32_e32 v18, 4, v5
	v_cmp_le_i32_e64 s[30:31], v19, v68
	v_or_b32_e32 v19, 12, v5
	v_cmp_le_i32_e64 s[48:49], v20, v68
	v_or_b32_e32 v20, 20, v5
	v_cmp_le_i32_e64 s[62:63], v21, v68
	v_or_b32_e32 v21, 27, v5
	v_lshl_add_u64 v[74:75], s[2:3], 0, v[66:67]
	s_andn2_b32 s1, s1, 63
	s_add_i32 s2, s89, 8
	s_add_i32 s3, s89, 16
	s_add_i32 s4, s89, 24
	v_lshl_or_b32 v12, s6, 6, v96
	s_lshl_b32 s74, s6, 10
	s_add_i32 s6, s89, 56
	v_cmp_le_i32_e64 s[16:17], v18, v68
	v_or_b32_e32 v18, 5, v5
	v_cmp_le_i32_e64 s[34:35], v19, v68
	v_or_b32_e32 v19, 13, v5
	v_cmp_le_i32_e64 s[50:51], v20, v68
	v_or_b32_e32 v20, 21, v5
	v_cmp_le_i32_e64 s[64:65], v21, v68
	v_or_b32_e32 v21, 28, v5
	v_or_b32_e32 v0, s1, v96
	v_lshl_or_b32 v2, s2, 6, v96
	v_lshl_or_b32 v4, s3, 6, v96
	v_lshl_or_b32 v6, s4, 6, v96
	v_lshl_or_b32 v14, s6, 6, v96
	v_cmp_le_i32_e64 s[18:19], v18, v68
	v_or_b32_e32 v18, 6, v5
	v_cmp_le_i32_e64 s[36:37], v19, v68
	v_or_b32_e32 v19, 14, v5
	v_cmp_le_i32_e64 s[52:53], v20, v68
	v_or_b32_e32 v20, 22, v5
	v_cmp_le_i32_e64 s[66:67], v21, v68
	v_or_b32_e32 v21, 29, v5
	v_and_b32_e32 v11, 15, v68
	v_ashrrev_i32_e32 v100, 5, v0
	v_ashrrev_i32_e32 v101, 5, v2
	v_ashrrev_i32_e32 v102, 5, v4
	v_ashrrev_i32_e32 v103, 5, v6
	v_ashrrev_i32_e32 v104, 5, v8
	v_ashrrev_i32_e32 v105, 5, v10
	v_ashrrev_i32_e32 v106, 5, v12
	v_ashrrev_i32_e32 v107, 5, v14
	s_lshl_b32 s75, s6, 10
	v_cmp_le_i32_e64 s[6:7], v5, v68
	v_cmp_lt_i32_e64 s[10:11], v5, v68
	v_cmp_le_i32_e64 s[20:21], v18, v68
	v_or_b32_e32 v18, 7, v5
	v_cmp_le_i32_e64 s[38:39], v19, v68
	v_or_b32_e32 v19, 15, v5
	v_cmp_le_i32_e64 s[54:55], v20, v68
	v_or_b32_e32 v20, 23, v5
	v_cmp_le_i32_e64 s[68:69], v21, v68
	v_or_b32_e32 v21, 30, v5
	v_or_b32_e32 v5, 31, v5
	v_and_b32_e32 v65, 31, v97
	v_and_b32_e32 v15, 8, v64
	v_and_b32_e32 v17, 15, v97
	v_lshlrev_b32_e32 v0, 2, v100
	v_lshlrev_b32_e32 v2, 2, v101
	v_lshlrev_b32_e32 v4, 2, v102
	v_lshlrev_b32_e32 v6, 2, v103
	v_lshlrev_b32_e32 v8, 2, v104
	v_lshlrev_b32_e32 v10, 2, v105
	v_lshlrev_b32_e32 v12, 2, v106
	v_lshlrev_b32_e32 v14, 2, v107
	v_cmp_le_i32_e64 s[22:23], v18, v68
	v_bitop3_b32 v18, v9, v68, 15 bitop3:0x78
	v_cmp_le_i32_e64 s[40:41], v19, v68
	v_bitop3_b32 v19, v9, v11, 1 bitop3:0x36
	v_cmp_le_i32_e64 s[56:57], v20, v68
	v_bitop3_b32 v20, v9, v11, 2 bitop3:0x36
	v_cmp_le_i32_e64 s[72:73], v5, v68
	v_bitop3_b32 v5, v9, v11, 3 bitop3:0x36
	v_lshlrev_b32_e32 v9, 12, v1
	v_bitop3_b32 v0, v0, v65, 12 bitop3:0x6c
	v_bitop3_b32 v2, v2, v65, 12 bitop3:0x6c
	v_bitop3_b32 v4, v4, v65, 12 bitop3:0x6c
	v_bitop3_b32 v6, v6, v65, 12 bitop3:0x6c
	v_bitop3_b32 v8, v8, v65, 12 bitop3:0x6c
	v_bitop3_b32 v10, v10, v65, 12 bitop3:0x6c
	v_bitop3_b32 v12, v12, v65, 12 bitop3:0x6c
	v_bitop3_b32 v14, v14, v65, 12 bitop3:0x6c
	v_cmp_le_i32_e64 s[70:71], v21, v68
	v_add3_u32 v9, v13, v15, v9
	v_bitop3_b32 v11, v1, v97, 15 bitop3:0x78
	v_bitop3_b32 v13, v1, v17, 2 bitop3:0x36
	v_bitop3_b32 v15, v1, v17, 4 bitop3:0x36
	v_bitop3_b32 v21, v1, v17, 6 bitop3:0x36
	v_bitop3_b32 v22, v1, v17, 8 bitop3:0x36
	v_bitop3_b32 v23, v1, v17, 10 bitop3:0x36
	v_bitop3_b32 v24, v1, v17, 12 bitop3:0x36
	v_bitop3_b32 v1, v1, v17, 14 bitop3:0x36
	v_lshlrev_b32_e32 v0, 3, v0
	s_lshl_b32 s1, s89, 10
	v_lshlrev_b32_e32 v2, 3, v2
	s_lshl_b32 s2, s2, 10
	v_lshlrev_b32_e32 v4, 3, v4
	s_lshl_b32 s3, s3, 10
	v_lshlrev_b32_e32 v6, 3, v6
	s_lshl_b32 s4, s4, 10
	v_lshlrev_b32_e32 v8, 3, v8
	v_lshlrev_b32_e32 v10, 3, v10
	v_lshlrev_b32_e32 v12, 3, v12
	v_lshlrev_b32_e32 v14, 3, v14
	v_lshlrev_b32_e32 v18, 4, v18
	v_lshlrev_b32_e32 v19, 4, v19
	v_lshlrev_b32_e32 v20, 4, v20
	v_lshlrev_b32_e32 v5, 4, v5
	v_lshlrev_b32_e32 v3, 9, v3
	v_lshlrev_b32_e32 v11, 4, v11
	v_lshlrev_b32_e32 v13, 4, v13
	v_lshlrev_b32_e32 v15, 4, v15
	v_lshlrev_b32_e32 v21, 4, v21
	v_lshlrev_b32_e32 v22, 4, v22
	v_lshlrev_b32_e32 v23, 4, v23
	v_lshlrev_b32_e32 v24, 4, v24
	v_lshlrev_b32_e32 v1, 4, v1
	v_ashrrev_i32_e32 v69, 31, v68
	v_or_b32_e32 v108, 32, v65
	v_or_b32_e32 v109, 64, v65
	v_or_b32_e32 v110, 0x60, v65
	s_lshl_b32 s85, s84, 4
	s_lshl_b32 s92, s0, 4
	v_lshlrev_b32_e32 v76, 1, v0
	s_add_i32 s93, s1, 0
	v_lshlrev_b32_e32 v66, 1, v2
	s_add_i32 s94, s2, 0
	v_lshlrev_b32_e32 v78, 1, v4
	s_add_i32 s95, s3, 0
	v_lshlrev_b32_e32 v80, 1, v6
	s_add_i32 s78, s4, 0
	v_lshlrev_b32_e32 v82, 1, v8
	s_add_i32 s79, s8, 0
	v_lshlrev_b32_e32 v84, 1, v10
	s_add_i32 s3, s9, 0
	v_lshlrev_b32_e32 v86, 1, v12
	s_add_i32 s76, s74, 0
	v_lshlrev_b32_e32 v88, 1, v14
	s_add_i32 s77, s75, 0
	v_mov_b32_e32 v111, 0x358637bd
	v_add_u32_e32 v112, v7, v18
	v_add_u32_e32 v113, v7, v19
	v_add_u32_e32 v114, v7, v20
	v_add_u32_e32 v115, v7, v5
	v_add_u32_e32 v116, v9, v3
	v_add_u32_e32 v117, v16, v11
	v_add_u32_e32 v118, v16, v13
	v_add_u32_e32 v119, v16, v15
	v_add_u32_e32 v120, v16, v21
	v_add_u32_e32 v121, v16, v22
	v_add_u32_e32 v122, v16, v23
	v_add_u32_e32 v123, v16, v24
	v_add_u32_e32 v124, v16, v1
	v_mov_b32_e32 v77, v67
	s_mov_b32 s90, s84
	s_barrier
	s_branch .LBB0_239

.LBB0_992:
	v_writelane_b32 v255, s66, 24
	s_nop 1
	v_writelane_b32 v255, s67, 25
	s_or_b64 exec, exec, s[4:5]
	s_waitcnt lgkmcnt(0)
	v_mov_b32_e32 v0, 0
	s_mov_b32 s4, 0
	v_mbcnt_lo_u32_b32 v0, -1, v0
	v_mbcnt_hi_u32_b32 v0, -1, v0
	v_add_u32_e32 v96, s33, v0
	s_ashr_i32 s5, s4, 31
	v_readfirstlane_b32 s1, v96
	s_ashr_i32 s3, s1, 6
	s_lshl_b64 s[4:5], s[4:5], 3
	v_readlane_b32 s6, v255, 2
	v_readlane_b32 s7, v255, 3
	s_add_u32 s4, s6, s4
	s_addc_u32 s5, s7, s5
	s_load_dwordx2 s[4:5], s[4:5], 0x38
	v_mov_b32_e32 v67, 0
	v_and_b32_e32 v97, 63, v96
	v_lshlrev_b32_e32 v64, 3, v96
	s_waitcnt lgkmcnt(0)
	s_add_u32 s4, s4, 0x2000
	s_addc_u32 s5, s5, 0
	v_writelane_b32 v255, s4, 20
	s_nop 1
	v_writelane_b32 v255, s5, 21
	s_mov_b32 s4, 0
	s_ashr_i32 s5, s4, 31
	s_lshl_b64 s[4:5], s[4:5], 3
	s_add_u32 s4, s6, s4
	s_addc_u32 s5, s7, s5
	s_load_dwordx2 s[4:5], s[4:5], 0x40
	s_waitcnt lgkmcnt(0)
	s_add_u32 s4, s4, 0x80000
	s_addc_u32 s5, s5, 0
	v_writelane_b32 v255, s4, 52
	s_nop 1
	v_writelane_b32 v255, s5, 53
	s_mov_b32 s4, 0
	s_ashr_i32 s5, s4, 31
	s_lshl_b64 s[4:5], s[4:5], 3
	s_add_u32 s4, s6, s4
	s_addc_u32 s5, s7, s5
	s_load_dwordx2 s[6:7], s[4:5], 0x48
	s_mov_b32 s5, 0
	s_waitcnt lgkmcnt(0)
	s_add_u32 s8, s6, 0x1000
	s_addc_u32 s9, s7, 0
	v_readlane_b32 s6, v255, 43
	v_readlane_b32 s7, v255, 44
	s_and_b64 vcc, exec, s[6:7]
	s_cbranch_vccz .Lmy_bsk9
	s_barrier
	s_branch .LBB0_1061
.Lmy_bsk9:
	v_and_b32_e32 v0, 3, v96
	v_lshlrev_b32_e32 v5, 5, v0
	v_lshlrev_b32_e32 v66, 7, v0
	v_lshlrev_b32_e32 v9, 2, v0
	v_lshrrev_b32_e32 v0, 3, v96
	s_lshl_b32 s4, s3, 2
	v_and_b32_e32 v0, 2, v0
	v_bfe_u32 v2, v96, 1, 1
	v_bfe_u32 v3, v96, 2, 2
	v_readlane_b32 s6, v255, 52
	v_or3_b32 v0, s4, v0, v2
	s_movk_i32 s2, 0x80
	v_readlane_b32 s7, v255, 53
	v_lshlrev_b32_e32 v2, 6, v3
	v_lshlrev_b32_e32 v0, 4, v0
	v_cmp_gt_i32_e32 vcc, s2, v96
	s_add_i32 s2, 0, 0x18000
	v_lshl_add_u64 v[70:71], s[6:7], 0, v[66:67]
	v_xad_u32 v13, v0, v2, 0
	v_lshlrev_b32_e32 v0, 8, v96
	s_lshl_b32 s6, s3, 5
	v_lshl_add_u32 v98, v96, 2, s2
	v_ashrrev_i32_e32 v68, 2, v96
	v_add_u32_e32 v99, s2, v66
	s_add_i32 s2, 0, 0x10000
	v_and_b32_e32 v0, 0x1f00, v0
	s_ashr_i32 s7, s6, 31
	v_lshl_add_u32 v7, v68, 8, s2
	v_add_u32_e32 v16, s2, v0
	s_lshl_b64 s[10:11], s[6:7], 1
	v_readlane_b32 s2, v255, 31
	v_lshrrev_b32_e32 v1, 5, v97
	s_add_u32 s10, s2, s10
	v_readlane_b32 s2, v255, 33
	s_addc_u32 s11, s2, s11
	v_lshlrev_b32_e32 v66, 3, v1
	v_or_b32_e32 v19, 8, v5
	v_or_b32_e32 v20, 16, v5
	v_lshl_add_u64 v[72:73], s[10:11], 0, v[66:67]
	s_lshl_b64 s[6:7], s[6:7], 2
	v_readlane_b32 s10, v255, 20
	v_cmp_le_i32_e64 s[28:29], v19, v68
	v_or_b32_e32 v19, 9, v5
	v_cmp_le_i32_e64 s[46:47], v20, v68
	v_or_b32_e32 v20, 17, v5
	v_or_b32_e32 v21, 24, v5
	v_readlane_b32 s11, v255, 21
	s_add_u32 s6, s10, s6
	v_or_b32_e32 v18, 2, v5
	v_cmp_le_i32_e64 s[30:31], v19, v68
	v_or_b32_e32 v19, 10, v5
	v_cmp_le_i32_e64 s[48:49], v20, v68
	v_or_b32_e32 v20, 18, v5
	v_cmp_le_i32_e64 s[62:63], v21, v68
	v_or_b32_e32 v21, 25, v5
	s_addc_u32 s7, s11, s7
	s_add_i32 s10, s3, 40
	v_cmp_le_i32_e64 s[16:17], v18, v68
	v_or_b32_e32 v18, 3, v5
	v_cmp_le_i32_e64 s[34:35], v19, v68
	v_or_b32_e32 v19, 11, v5
	v_cmp_le_i32_e64 s[50:51], v20, v68
	v_or_b32_e32 v20, 19, v5
	v_cmp_le_i32_e64 s[64:65], v21, v68
	v_or_b32_e32 v21, 26, v5
	v_lshlrev_b32_e32 v66, 4, v1
	v_lshl_or_b32 v10, s10, 6, v97
	s_lshl_b32 s78, s10, 10
	s_add_i32 s10, s3, 48
	v_cmp_le_i32_e64 s[18:19], v18, v68
	v_or_b32_e32 v18, 4, v5
	v_cmp_le_i32_e64 s[36:37], v19, v68
	v_or_b32_e32 v19, 12, v5
	v_cmp_le_i32_e64 s[52:53], v20, v68
	v_or_b32_e32 v20, 20, v5
	v_cmp_le_i32_e64 s[66:67], v21, v68
	v_or_b32_e32 v21, 27, v5
	v_lshl_add_u64 v[74:75], s[6:7], 0, v[66:67]
	s_andn2_b32 s1, s1, 63
	s_add_i32 s2, s3, 8
	s_add_i32 s4, s3, 16
	s_add_i32 s6, s3, 24
	s_add_i32 s7, s3, 32
	v_lshl_or_b32 v12, s10, 6, v97
	s_lshl_b32 s79, s10, 10
	s_add_i32 s10, s3, 56
	v_cmp_le_i32_e64 s[20:21], v18, v68
	v_or_b32_e32 v18, 5, v5
	v_cmp_le_i32_e64 s[38:39], v19, v68
	v_or_b32_e32 v19, 13, v5
	v_cmp_le_i32_e64 s[54:55], v20, v68
	v_or_b32_e32 v20, 21, v5
	v_cmp_le_i32_e64 s[68:69], v21, v68
	v_or_b32_e32 v21, 28, v5
	v_or_b32_e32 v0, s1, v97
	v_lshl_or_b32 v2, s2, 6, v97
	v_lshl_or_b32 v4, s4, 6, v97
	v_lshl_or_b32 v6, s6, 6, v97
	v_lshl_or_b32 v8, s7, 6, v97
	v_lshl_or_b32 v14, s10, 6, v97
	v_cmp_le_i32_e64 s[22:23], v18, v68
	v_or_b32_e32 v18, 6, v5
	v_cmp_le_i32_e64 s[40:41], v19, v68
	v_or_b32_e32 v19, 14, v5
	v_cmp_le_i32_e64 s[56:57], v20, v68
	v_or_b32_e32 v20, 22, v5
	v_cmp_le_i32_e64 s[70:71], v21, v68
	v_or_b32_e32 v21, 29, v5
	v_and_b32_e32 v11, 15, v68
	v_ashrrev_i32_e32 v100, 5, v0
	v_ashrrev_i32_e32 v101, 5, v2
	v_ashrrev_i32_e32 v102, 5, v4
	v_ashrrev_i32_e32 v103, 5, v6
	v_ashrrev_i32_e32 v104, 5, v8
	v_ashrrev_i32_e32 v105, 5, v10
	v_ashrrev_i32_e32 v106, 5, v12
	v_ashrrev_i32_e32 v107, 5, v14
	v_cmp_le_i32_e64 s[12:13], v5, v68
	v_cmp_lt_i32_e64 s[14:15], v5, v68
	v_cmp_le_i32_e64 s[24:25], v18, v68
	v_or_b32_e32 v18, 7, v5
	v_cmp_le_i32_e64 s[42:43], v19, v68
	v_or_b32_e32 v19, 15, v5
	v_cmp_le_i32_e64 s[58:59], v20, v68
	v_or_b32_e32 v20, 23, v5
	v_cmp_le_i32_e64 s[72:73], v21, v68
	v_or_b32_e32 v21, 30, v5
	v_or_b32_e32 v5, 31, v5
	v_and_b32_e32 v65, 31, v96
	v_and_b32_e32 v15, 8, v64
	v_and_b32_e32 v17, 15, v96
	v_lshlrev_b32_e32 v0, 2, v100
	v_lshlrev_b32_e32 v2, 2, v101
	v_lshlrev_b32_e32 v4, 2, v102
	v_lshlrev_b32_e32 v6, 2, v103
	v_lshlrev_b32_e32 v8, 2, v104
	v_lshlrev_b32_e32 v10, 2, v105
	v_lshlrev_b32_e32 v12, 2, v106
	v_lshlrev_b32_e32 v14, 2, v107
	v_cmp_le_i32_e64 s[26:27], v18, v68
	v_bitop3_b32 v18, v9, v68, 15 bitop3:0x78
	v_cmp_le_i32_e64 s[44:45], v19, v68
	v_bitop3_b32 v19, v9, v11, 1 bitop3:0x36
	v_cmp_le_i32_e64 s[60:61], v20, v68
	v_bitop3_b32 v20, v9, v11, 2 bitop3:0x36
	v_cmp_le_i32_e64 s[76:77], v5, v68
	v_bitop3_b32 v5, v9, v11, 3 bitop3:0x36
	v_lshlrev_b32_e32 v9, 12, v1
	v_bitop3_b32 v0, v0, v65, 12 bitop3:0x6c
	v_bitop3_b32 v2, v2, v65, 12 bitop3:0x6c
	v_bitop3_b32 v4, v4, v65, 12 bitop3:0x6c
	v_bitop3_b32 v6, v6, v65, 12 bitop3:0x6c
	v_bitop3_b32 v8, v8, v65, 12 bitop3:0x6c
	v_bitop3_b32 v10, v10, v65, 12 bitop3:0x6c
	v_bitop3_b32 v12, v12, v65, 12 bitop3:0x6c
	v_bitop3_b32 v14, v14, v65, 12 bitop3:0x6c
	s_lshl_b32 s84, s10, 10
	v_cmp_le_i32_e64 s[74:75], v21, v68
	v_add3_u32 v9, v13, v15, v9
	v_bitop3_b32 v11, v1, v96, 15 bitop3:0x78
	v_bitop3_b32 v13, v1, v17, 2 bitop3:0x36
	v_bitop3_b32 v15, v1, v17, 4 bitop3:0x36
	v_bitop3_b32 v21, v1, v17, 6 bitop3:0x36
	v_bitop3_b32 v22, v1, v17, 8 bitop3:0x36
	v_bitop3_b32 v23, v1, v17, 10 bitop3:0x36
	v_bitop3_b32 v24, v1, v17, 12 bitop3:0x36
	v_bitop3_b32 v1, v1, v17, 14 bitop3:0x36
	v_readlane_b32 s10, v255, 24
	v_lshlrev_b32_e32 v0, 3, v0
	s_lshl_b32 s1, s3, 10
	v_lshlrev_b32_e32 v2, 3, v2
	s_lshl_b32 s2, s2, 10
	v_lshlrev_b32_e32 v4, 3, v4
	s_lshl_b32 s4, s4, 10
	v_lshlrev_b32_e32 v6, 3, v6
	s_lshl_b32 s6, s6, 10
	v_lshlrev_b32_e32 v8, 3, v8
	s_lshl_b32 s7, s7, 10
	v_lshlrev_b32_e32 v10, 3, v10
	v_lshlrev_b32_e32 v12, 3, v12
	v_lshlrev_b32_e32 v14, 3, v14
	v_lshlrev_b32_e32 v18, 4, v18
	v_lshlrev_b32_e32 v19, 4, v19
	v_lshlrev_b32_e32 v20, 4, v20
	v_lshlrev_b32_e32 v5, 4, v5
	v_lshlrev_b32_e32 v3, 9, v3
	v_lshlrev_b32_e32 v11, 4, v11
	v_lshlrev_b32_e32 v13, 4, v13
	v_lshlrev_b32_e32 v15, 4, v15
	v_lshlrev_b32_e32 v21, 4, v21
	v_lshlrev_b32_e32 v22, 4, v22
	v_lshlrev_b32_e32 v23, 4, v23
	v_lshlrev_b32_e32 v24, 4, v24
	v_lshlrev_b32_e32 v1, 4, v1
	v_readlane_b32 s11, v255, 25
	s_mov_b32 s88, s10
	v_ashrrev_i32_e32 v69, 31, v68
	v_or_b32_e32 v108, 32, v65
	v_or_b32_e32 v109, 64, v65
	v_or_b32_e32 v110, 0x60, v65
	s_lshl_b32 s85, s10, 4
	s_lshl_b32 s94, s0, 4
	v_lshlrev_b32_e32 v76, 1, v0
	s_add_i32 s95, s1, 0
	v_lshlrev_b32_e32 v66, 1, v2
	s_add_i32 s10, s2, 0
	v_lshlrev_b32_e32 v78, 1, v4
	s_add_i32 s11, s4, 0
	v_lshlrev_b32_e32 v80, 1, v6
	s_add_i32 s86, s6, 0
	v_lshlrev_b32_e32 v82, 1, v8
	s_add_i32 s87, s7, 0
	v_lshlrev_b32_e32 v84, 1, v10
	s_add_i32 s6, s78, 0
	v_lshlrev_b32_e32 v86, 1, v12
	s_add_i32 s7, s79, 0
	v_lshlrev_b32_e32 v88, 1, v14
	s_add_i32 s92, s84, 0
	v_mov_b32_e32 v111, 0x358637bd
	v_add_u32_e32 v112, v7, v18
	v_add_u32_e32 v113, v7, v19
	v_add_u32_e32 v114, v7, v20
	v_add_u32_e32 v115, v7, v5
	v_add_u32_e32 v116, v9, v3
	v_add_u32_e32 v117, v16, v11
	v_add_u32_e32 v118, v16, v13
	v_add_u32_e32 v119, v16, v15
	v_add_u32_e32 v120, v16, v21
	v_add_u32_e32 v121, v16, v22
	v_add_u32_e32 v122, v16, v23
	v_add_u32_e32 v123, v16, v24
	v_add_u32_e32 v124, v16, v1
	v_mov_b32_e32 v77, v67
	s_mov_b32 s93, s88
	s_barrier
	s_branch .LBB0_995

.Lmy_bsk16:
	s_ashr_i32 s7, s6, 31
	s_lshl_b64 s[6:7], s[6:7], 3
	v_readlane_b32 s8, v255, 2
	v_readlane_b32 s9, v255, 3
	s_add_u32 s6, s8, s6
	s_addc_u32 s7, s9, s7
	s_load_dwordx2 s[6:7], s[6:7], 0x80
	v_and_b32_e32 v2, 63, v0
	v_mov_b32_e32 v9, v1
	v_lshlrev_b32_e32 v8, 4, v2
	v_mov_b32_e32 v3, 0x500
	s_waitcnt lgkmcnt(0)
	v_lshl_add_u64 v[4:5], s[6:7], 0, v[8:9]
	v_lshlrev_b32_e32 v12, 3, v2
	v_mov_b32_e32 v13, v1
	v_mad_i64_i32 v[8:9], s[12:13], s4, v3, v[8:9]
	v_lshlrev_b32_e32 v0, 2, v2
	v_mad_i64_i32 v[6:7], s[8:9], s4, v3, v[12:13]
	s_mov_b64 s[12:13], 0x264f7300
	v_mov_b32_e32 v3, 0x280
	v_lshl_add_u64 v[8:9], v[8:9], 0, s[12:13]
	v_mad_i64_i32 v[10:11], s[12:13], s4, v3, v[0:1]
	s_mov_b64 s[12:13], 0x27947500
	s_nop 0
	v_lshl_add_u64 v[10:11], v[10:11], 0, s[12:13]
	v_mad_i64_i32 v[12:13], s[12:13], s4, v3, v[12:13]
	s_lshl_b32 s6, s0, 3
	s_lshl_b32 s2, s84, 8
	s_lshl_b32 s1, s1, 5
	s_ashr_i32 s5, s4, 31
	s_mov_b64 s[12:13], 0x27947300
	s_add_i32 s1, s2, s1
	s_lshl_b32 s2, s0, 8
	s_ashr_i32 s7, s6, 31
	v_lshl_add_u64 v[12:13], v[12:13], 0, s[12:13]
	s_lshl_b64 s[12:13], s[4:5], 7
	s_mov_b64 s[8:9], 0x264f7700
	s_add_u32 s11, s12, 0x34ff7300
	v_cmp_gt_u32_e32 vcc, 32, v2
	v_lshl_add_u64 v[6:7], v[6:7], 0, s[8:9]
	s_mul_i32 s8, s0, 0x2800
	s_mul_hi_i32 s9, s6, 0x500
	s_mul_i32 s14, s0, 0x1400
	s_mul_hi_i32 s15, s6, 0x280
	s_addc_u32 s22, s13, 0
	s_lshl_b64 s[16:17], s[6:7], 7
	v_mov_b32_e32 v3, 0x358637bd
	s_mov_b32 s23, 0x800000
	s_mov_b32 s24, 0x4080000
	v_lshlrev_b32_e32 v0, 2, v0
	s_mov_b32 s25, 0x5080000
	v_lshlrev_b32_e32 v14, 2, v2
	s_barrier
	s_branch .LBB0_1971

.Lmy_bsk35:
	s_ashr_i32 s7, s6, 31
	s_lshl_b64 s[6:7], s[6:7], 3
	v_readlane_b32 s8, v255, 2
	v_readlane_b32 s9, v255, 3
	s_add_u32 s6, s8, s6
	s_addc_u32 s7, s9, s7
	s_load_dwordx2 s[6:7], s[6:7], 0xb8
	v_lshlrev_b32_e32 v4, 2, v12
	v_and_b32_e32 v14, 0xfc, v4
	v_readlane_b32 s8, v255, 39
	v_lshlrev_b32_e32 v0, 2, v14
	v_readlane_b32 s9, v255, 40
	s_movk_i32 s1, 0x80
	v_bfrev_b32_e32 v5, 0.5
	v_lshl_add_u64 v[2:3], s[8:9], 0, v[0:1]
	v_bitop3_b32 v30, v4, s1, v5 bitop3:0x6c
	v_bitop3_b32 v31, v4, 64, v5 bitop3:0x6c
	v_bitop3_b32 v32, v4, 32, v5 bitop3:0x6c
	v_bitop3_b32 v33, v4, 16, v5 bitop3:0x6c
	v_bitop3_b32 v34, v4, 8, v5 bitop3:0x6c
	v_bitop3_b32 v35, v4, 4, v5 bitop3:0x6c
	s_waitcnt lgkmcnt(0)
	v_lshl_add_u64 v[4:5], s[6:7], 0, v[0:1]
	s_lshl_b32 s6, s0, 3
	v_or_b32_e32 v6, 0x400, v0
	v_or_b32_e32 v8, 0x800, v0
	v_or_b32_e32 v0, 0xc00, v0
	s_ashr_i32 s5, s4, 31
	v_mov_b32_e32 v7, v1
	v_mov_b32_e32 v9, v1
	v_lshl_add_u64 v[10:11], s[8:9], 0, v[0:1]
	s_ashr_i32 s7, s6, 31
	s_lshl_b64 s[0:1], s[4:5], 11
	v_and_b32_e32 v0, 63, v12
	v_lshl_add_u64 v[6:7], s[8:9], 0, v[6:7]
	v_lshl_add_u64 v[8:9], s[8:9], 0, v[8:9]
	s_lshl_b64 s[8:9], s[4:5], 7
	s_lshl_b64 s[10:11], s[6:7], 7
	v_lshl_or_b32 v12, v0, 3, s0
	v_mov_b32_e32 v13, s1
	s_lshl_b64 s[12:13], s[6:7], 11
	v_mov_b32_e32 v0, 0x34ff7000
	v_mov_b32_e32 v36, 0x358637bd
	s_mov_b32 s18, 0x800000
	v_lshlrev_b32_e32 v37, 2, v14
	s_barrier
	global_load_dwordx4 v[100:103], v[4:5], off
	global_load_dwordx4 v[104:107], v[4:5], off offset:1024
	global_load_dwordx4 v[108:111], v[4:5], off offset:2048
	global_load_dwordx4 v[112:115], v[4:5], off offset:3072
	s_cmpk_lt_i32 s4, 0x4000
	s_cbranch_scc0 .LBB0_4349
